# attn tile loop: K/V register sets ping-pong, tile g+2 prefetched into the freed set, no per-tile copies; g3 epilogue loads hoisted
# baseline (speedup 1.0000x reference)
; DI void dsa_attn_item(const Params& p, int b, int qblk, char* smem) {
;     ...
;   u16* y = (u16*)(p.ws + OFF_XB);
;   {
;     float lt = lrun + __shfl_xor(lrun, 32);
;     float inv = 1.f / lt;
; #pragma unroll
;     for (int dt = 0; dt < 2; ++dt)
; #pragma unroll
;       for (int g = 0; g < 4; ++g)
;         st4bf(y + (size_t)qtok * 1024 + head * 64 + dt * 32 + 8 * g + 4 * lh, O[dt][4 * g] * inv, O[dt][4 * g + 1] * inv, O[dt][4 * g + 2] * inv, O[dt][4 * g + 3] * inv);
;   }
;   __syncthreads();
.LBB0_424:
	s_waitcnt vmcnt(0)
	v_xor_b32_e32 v0, 32, v177
	v_add_u32_e32 v34, 64, v179
	v_cmp_lt_i32_e32 vcc, v0, v34
	v_lshlrev_b64 v[34:35], 11, v[196:197]
	v_lshl_add_u64 v[34:35], v[188:189], 0, v[34:35]
	v_cndmask_b32_e32 v0, v177, v0, vcc
	v_lshlrev_b32_e32 v0, 2, v0
	ds_bpermute_b32 v0, v0, v171
	s_waitcnt lgkmcnt(0)
	v_add_f32_e32 v0, v171, v0
	v_div_scale_f32 v36, s[0:1], v0, v0, 1.0
	v_rcp_f32_e32 v37, v36
	v_div_scale_f32 v38, vcc, 1.0, v0, 1.0
	v_fma_f32 v39, -v36, v37, 1.0
	v_fmac_f32_e32 v37, v39, v37
	v_mul_f32_e32 v39, v38, v37
	v_fma_f32 v40, -v36, v39, v38
	v_fmac_f32_e32 v39, v40, v37
	v_fma_f32 v36, -v36, v39, v38
	v_div_fmas_f32 v36, v36, v37, v39
	v_div_fixup_f32 v0, v36, v0, 1.0
	v_pk_mul_f32 v[18:19], v[18:19], v[0:1] op_sel_hi:[1,0]
	v_pk_mul_f32 v[20:21], v[20:21], v[0:1] op_sel_hi:[1,0]
	v_pk_mul_f32 v[2:3], v[2:3], v[0:1] op_sel_hi:[1,0]
	v_pk_mul_f32 v[4:5], v[4:5], v[0:1] op_sel_hi:[1,0]
	v_cvt_pk_bf16_f32 v18, v18, v19
	v_cvt_pk_bf16_f32 v19, v20, v21
	v_cvt_pk_bf16_f32 v2, v2, v3
	v_cvt_pk_bf16_f32 v3, v4, v5
	global_store_dwordx2 v[34:35], v[18:19], off
	v_pk_mul_f32 v[18:19], v[22:23], v[0:1] op_sel_hi:[1,0]
	v_pk_mul_f32 v[20:21], v[24:25], v[0:1] op_sel_hi:[1,0]
	global_store_dwordx2 v[34:35], v[2:3], off offset:64
	v_pk_mul_f32 v[2:3], v[6:7], v[0:1] op_sel_hi:[1,0]
	v_pk_mul_f32 v[4:5], v[8:9], v[0:1] op_sel_hi:[1,0]
	v_cvt_pk_bf16_f32 v18, v18, v19
	v_cvt_pk_bf16_f32 v19, v20, v21
	v_cvt_pk_bf16_f32 v2, v2, v3
	v_cvt_pk_bf16_f32 v3, v4, v5
	global_store_dwordx2 v[34:35], v[18:19], off offset:16
	v_pk_mul_f32 v[18:19], v[26:27], v[0:1] op_sel_hi:[1,0]
	v_pk_mul_f32 v[20:21], v[28:29], v[0:1] op_sel_hi:[1,0]
	global_store_dwordx2 v[34:35], v[2:3], off offset:80
	v_pk_mul_f32 v[2:3], v[10:11], v[0:1] op_sel_hi:[1,0]
	v_pk_mul_f32 v[4:5], v[12:13], v[0:1] op_sel_hi:[1,0]
	v_cvt_pk_bf16_f32 v18, v18, v19
	v_cvt_pk_bf16_f32 v19, v20, v21
	v_cvt_pk_bf16_f32 v2, v2, v3
	v_cvt_pk_bf16_f32 v3, v4, v5
	global_store_dwordx2 v[34:35], v[18:19], off offset:32
	v_pk_mul_f32 v[18:19], v[30:31], v[0:1] op_sel_hi:[1,0]
	v_pk_mul_f32 v[20:21], v[32:33], v[0:1] op_sel_hi:[1,0]
	global_store_dwordx2 v[34:35], v[2:3], off offset:96
	v_pk_mul_f32 v[2:3], v[14:15], v[0:1] op_sel_hi:[1,0]
	v_pk_mul_f32 v[4:5], v[16:17], v[0:1] op_sel_hi:[1,0]
	v_cvt_pk_bf16_f32 v18, v18, v19
	v_cvt_pk_bf16_f32 v19, v20, v21
	v_cvt_pk_bf16_f32 v2, v2, v3
	v_cvt_pk_bf16_f32 v3, v4, v5
	global_store_dwordx2 v[34:35], v[18:19], off offset:48
	global_store_dwordx2 v[34:35], v[2:3], off offset:112
	s_barrier

; #define MFMA(a, b, c) __builtin_amdgcn_mfma_f32_32x32x16_bf16((a), (b), (c), 0, 0, 0)
; DI f32x16 zero16() { f32x16 z; for (int i = 0; i < 16; ++i) z[i] = 0.f; return z; }
; DI void dsa_attn_item(const Params& p, int b, int qblk, char* smem) {
;     ...
;     for (int t8 = 0; t8 < 8; ++t8) {
;       const int g = c * 8 + t8;
;       if (g > qblk) break;
;       {
;         const int gn = min(g + 1, qblk);
;         const u16* kr = kfr + (size_t)gn * 2048;
; #pragma unroll
;         for (int ks = 0; ks < 4; ++ks) Kn[ks] = ldg8(kr + ks * 512);
; #pragma unroll
;         for (int dt = 0; dt < 2; ++dt)
; #pragma unroll
;           for (int s = 0; s < 2; ++s) Vn[dt][s] = ldg8(vfr + (size_t)gn * 2048 + (dt * 2 + s) * 512);
;       }
;       const unsigned bits = maskbuf[(buf * 8 + t8) * 64 + lane];
;       f32x16 Sx = zero16();
;       __builtin_amdgcn_s_setprio(1);
; #pragma unroll
;       for (int ks = 0; ks < 4; ++ks) Sx = MFMA(Kf[ks], Qf[ks], Sx);
;       __builtin_amdgcn_s_setprio(0);
;       float sm[16];
; #pragma unroll
;       for (int i = 0; i < 16; ++i) {
;         const unsigned t = (unsigned)__builtin_amdgcn_sbfe((int)bits, i, 1);
;         sm[i] = __uint_as_float((t & __float_as_uint(Sx[i])) | (~t & 0xff800000u));
;       }
;       float mt = fmaxf(fmaxf(fmaxf(sm[0], sm[1]), fmaxf(sm[2], sm[3])), fmaxf(fmaxf(sm[4], sm[5]), fmaxf(sm[6], sm[7])));
;       mt = fmaxf(mt, fmaxf(fmaxf(fmaxf(sm[8], sm[9]), fmaxf(sm[10], sm[11])), fmaxf(fmaxf(sm[12], sm[13]), fmaxf(sm[14], sm[15]))));
;       mt = fmaxf(mt, __shfl_xor(mt, 32));
;       if (__builtin_amdgcn_ballot_w64(mt > mrun + 8.f) != 0ull) {
;         const float mnew = fmaxf(mrun, mt);
;         const float ms = (mnew == -INFINITY) ? 0.f : mnew;
;         const float alpha = __builtin_amdgcn_exp2f(mrun - ms);
;         lrun *= alpha;
;         mrun = mnew;
; #pragma unroll
;         for (int dt = 0; dt < 2; ++dt)
; #pragma unroll
;           for (int i = 0; i < 16; ++i) O[dt][i] *= alpha;
;       }
.LBB0_439:
	s_add_i32 s60, s53, 1
	s_min_i32 s40, s60, s52
	s_lshl_b64 s[10:11], s[40:41], 12
	v_lshl_add_u64 v[252:253], v[198:199], 0, s[10:11]
	global_load_dwordx4 v[66:69], v[252:253], off
	global_load_dwordx4 v[70:73], v[252:253], off offset:1024
	global_load_dwordx4 v[74:77], v[252:253], off offset:2048
	global_load_dwordx4 v[78:81], v[252:253], off offset:3072
	v_lshl_add_u64 v[252:253], v[200:201], 0, s[10:11]
	global_load_dwordx4 v[50:53], v[252:253], off
	global_load_dwordx4 v[54:57], v[252:253], off offset:1024
	global_load_dwordx4 v[58:61], v[252:253], off offset:2048
	global_load_dwordx4 v[62:65], v[252:253], off offset:3072
.Lattn_hdrA:
	s_add_i32 s7, s53, s6
	s_cmp_le_u32 s7, s52
	s_cselect_b64 s[0:1], -1, 0
	s_cmp_gt_u32 s7, s52
	s_cbranch_scc1 .LBB0_446
	s_add_i32 s60, s7, 2
	s_min_i32 s40, s60, s52
	s_lshl_b64 s[10:11], s[40:41], 12
	s_waitcnt vmcnt(12)
	ds_read_u16 v154, v0
	s_setprio 1
	v_mfma_f32_32x32x16_bf16 v[34:49], v[150:153], v[98:101], 0
	v_mfma_f32_32x32x16_bf16 v[34:49], v[146:149], v[102:105], v[34:49]
	v_mfma_f32_32x32x16_bf16 v[34:49], v[142:145], v[106:109], v[34:49]
	v_mfma_f32_32x32x16_bf16 v[34:49], v[138:141], v[110:113], v[34:49]
	s_setprio 0
	s_cmp_lt_u32 s6, 7
	s_cbranch_scc0 .Lattn_nokA
	v_lshl_add_u64 v[252:253], v[198:199], 0, s[10:11]
	global_load_dwordx4 v[150:153], v[252:253], off
	global_load_dwordx4 v[146:149], v[252:253], off offset:1024
	global_load_dwordx4 v[142:145], v[252:253], off offset:2048
	global_load_dwordx4 v[138:141], v[252:253], off offset:3072
.Lattn_nokA:
	s_waitcnt lgkmcnt(0)
	v_bfe_i32 v238, v154, 0, 1
	v_bfe_i32 v239, v154, 1, 1
	v_bfe_i32 v240, v154, 2, 1
	v_bfe_i32 v241, v154, 3, 1
	v_bfe_i32 v242, v154, 4, 1
	v_bfe_i32 v243, v154, 5, 1
	v_bfe_i32 v244, v154, 6, 1
	v_bfe_i32 v245, v154, 7, 1
	v_bfe_i32 v246, v154, 8, 1
	v_bfe_i32 v247, v154, 9, 1
	v_bfe_i32 v248, v154, 10, 1
	v_bfe_i32 v249, v154, 11, 1
	v_bfe_i32 v250, v154, 12, 1
	v_bfe_i32 v251, v154, 13, 1
	v_bfe_i32 v252, v154, 14, 1
	v_bfe_i32 v253, v154, 15, 1
	v_bitop3_b32 v34, v34, s50, v238 bitop3:0xe4
	v_bitop3_b32 v35, v35, s50, v239 bitop3:0xe4
	v_bitop3_b32 v36, v36, s50, v240 bitop3:0xe4
	v_bitop3_b32 v37, v37, s50, v241 bitop3:0xe4
	v_bitop3_b32 v38, v38, s50, v242 bitop3:0xe4
	v_bitop3_b32 v39, v39, s50, v243 bitop3:0xe4
	v_bitop3_b32 v40, v40, s50, v244 bitop3:0xe4
	v_bitop3_b32 v41, v41, s50, v245 bitop3:0xe4
	v_bitop3_b32 v42, v42, s50, v246 bitop3:0xe4
	v_bitop3_b32 v43, v43, s50, v247 bitop3:0xe4
	v_bitop3_b32 v44, v44, s50, v248 bitop3:0xe4
	v_bitop3_b32 v45, v45, s50, v249 bitop3:0xe4
	v_bitop3_b32 v46, v46, s50, v250 bitop3:0xe4
	v_bitop3_b32 v47, v47, s50, v251 bitop3:0xe4
	v_bitop3_b32 v48, v48, s50, v252 bitop3:0xe4
	v_bitop3_b32 v49, v49, s50, v253 bitop3:0xe4
	v_max_f32_e32 v238, v36, v37
	v_max_f32_e32 v239, v40, v41
	v_max_f32_e32 v240, v42, v43
	v_max_f32_e32 v241, v44, v45
	v_max_f32_e32 v242, v48, v49
	v_max3_f32 v242, v46, v47, v242
	v_max3_f32 v238, v34, v35, v238
	v_max3_f32 v239, v38, v39, v239
	v_max3_f32 v240, v240, v241, v242
	v_max3_f32 v238, v238, v239, v240
	v_mov_b32_e32 v239, v238
	s_nop 1
	v_permlane32_swap_b32_e32 v239, v238
	v_max_f32_e32 v238, v238, v239
	v_add_f32_e32 v239, 0x41000000, v193
	v_cmp_gt_f32_e32 vcc, v238, v239
	s_cbranch_vccz .Lattn_442A
	v_max_f32_e32 v238, v238, v238
	v_max_f32_e32 v239, v193, v193
	v_max_f32_e32 v239, v239, v238
	v_cmp_neq_f32_e32 vcc, s50, v239
	s_nop 1
	v_cndmask_b32_e32 v238, 0, v239, vcc
	v_sub_f32_e32 v238, v193, v238
	v_exp_f32_e32 v238, v238
	v_mov_b32_e32 v193, v239
	v_pk_mul_f32 v[32:33], v[32:33], v[238:239] op_sel_hi:[1,0]
	v_pk_mul_f32 v[30:31], v[30:31], v[238:239] op_sel_hi:[1,0]
	v_pk_mul_f32 v[28:29], v[28:29], v[238:239] op_sel_hi:[1,0]
	v_pk_mul_f32 v[26:27], v[26:27], v[238:239] op_sel_hi:[1,0]
	v_pk_mul_f32 v[24:25], v[24:25], v[238:239] op_sel_hi:[1,0]
	v_pk_mul_f32 v[22:23], v[22:23], v[238:239] op_sel_hi:[1,0]
	v_pk_mul_f32 v[20:21], v[20:21], v[238:239] op_sel_hi:[1,0]
	v_pk_mul_f32 v[18:19], v[18:19], v[238:239] op_sel_hi:[1,0]
	v_pk_mul_f32 v[16:17], v[16:17], v[238:239] op_sel_hi:[1,0]
	v_pk_mul_f32 v[14:15], v[14:15], v[238:239] op_sel_hi:[1,0]
	v_pk_mul_f32 v[12:13], v[12:13], v[238:239] op_sel_hi:[1,0]
	v_pk_mul_f32 v[10:11], v[10:11], v[238:239] op_sel_hi:[1,0]
	v_pk_mul_f32 v[8:9], v[8:9], v[238:239] op_sel_hi:[1,0]
	v_pk_mul_f32 v[6:7], v[6:7], v[238:239] op_sel_hi:[1,0]
	v_pk_mul_f32 v[4:5], v[4:5], v[238:239] op_sel_hi:[1,0]
	v_pk_mul_f32 v[2:3], v[2:3], v[238:239] op_sel_hi:[1,0]
	v_mul_f32_e32 v171, v171, v238
; #define MFMA(a, b, c) __builtin_amdgcn_mfma_f32_32x32x16_bf16((a), (b), (c), 0, 0, 0)
; DI void dsa_attn_item(const Params& p, int b, int qblk, char* smem) {
;     ...
;       const float msafe = (mrun == -INFINITY) ? 0.f : mrun;
;       float pv[16]; float ps = 0.f;
; #pragma unroll
;       for (int i = 0; i < 16; ++i) { pv[i] = __builtin_amdgcn_exp2f(sm[i] - msafe); ps += pv[i]; }
;       lrun += ps;
;       bf16x8 Pf[2];
; #pragma unroll
;       for (int s = 0; s < 2; ++s) Pf[s] = pack8(pv[8 * s], pv[8 * s + 1], pv[8 * s + 2], pv[8 * s + 3], pv[8 * s + 4], pv[8 * s + 5], pv[8 * s + 6], pv[8 * s + 7]);
;       __builtin_amdgcn_s_setprio(1);
; #pragma unroll
;       for (int dt = 0; dt < 2; ++dt)
; #pragma unroll
;         for (int s = 0; s < 2; ++s) O[dt] = MFMA(Vf[dt][s], Pf[s], O[dt]);
;       __builtin_amdgcn_s_setprio(0);
; #pragma unroll
;       for (int ks = 0; ks < 4; ++ks) Kf[ks] = Kn[ks];
; #pragma unroll
;       for (int dt = 0; dt < 2; ++dt)
; #pragma unroll
;         for (int s = 0; s < 2; ++s) Vf[dt][s] = Vn[dt][s];
;     }
.Lattn_442A:
	v_cmp_neq_f32_e32 vcc, s50, v193
	s_nop 1
	v_cndmask_b32_e32 v238, 0, v193, vcc
	v_sub_f32_e32 v34, v34, v238
	v_exp_f32_e32 v239, v34
	v_sub_f32_e32 v34, v35, v238
	v_exp_f32_e32 v240, v34
	v_sub_f32_e32 v34, v36, v238
	v_exp_f32_e32 v241, v34
	v_sub_f32_e32 v34, v37, v238
	v_exp_f32_e32 v242, v34
	v_sub_f32_e32 v34, v38, v238
	v_exp_f32_e32 v243, v34
	v_sub_f32_e32 v34, v39, v238
	v_exp_f32_e32 v244, v34
	v_sub_f32_e32 v34, v40, v238
	v_exp_f32_e32 v245, v34
	v_sub_f32_e32 v34, v41, v238
	v_exp_f32_e32 v246, v34
	v_sub_f32_e32 v34, v42, v238
	v_exp_f32_e32 v42, v34
	v_sub_f32_e32 v34, v43, v238
	v_exp_f32_e32 v43, v34
	v_sub_f32_e32 v34, v44, v238
	v_exp_f32_e32 v44, v34
	v_sub_f32_e32 v34, v45, v238
	v_exp_f32_e32 v45, v34
	v_sub_f32_e32 v34, v46, v238
	v_exp_f32_e32 v46, v34
	v_sub_f32_e32 v34, v47, v238
	v_exp_f32_e32 v47, v34
	v_sub_f32_e32 v34, v48, v238
	v_exp_f32_e32 v48, v34
	v_sub_f32_e32 v34, v49, v238
	v_add_f32_e32 v238, 0, v239
	v_add_f32_e32 v238, v240, v238
	v_add_f32_e32 v238, v241, v238
	v_add_f32_e32 v238, v242, v238
	v_add_f32_e32 v238, v243, v238
	v_add_f32_e32 v238, v244, v238
	v_add_f32_e32 v238, v245, v238
	v_add_f32_e32 v238, v246, v238
	v_cvt_pk_bf16_f32 v38, v42, v43
	v_add_f32_e32 v42, v42, v238
	v_add_f32_e32 v42, v43, v42
	v_add_f32_e32 v42, v44, v42
	v_exp_f32_e32 v49, v34
	v_add_f32_e32 v42, v45, v42
	v_add_f32_e32 v42, v46, v42
	v_add_f32_e32 v42, v47, v42
	v_add_f32_e32 v42, v48, v42
	v_cvt_pk_bf16_f32 v34, v239, v240
	v_cvt_pk_bf16_f32 v35, v241, v242
	v_cvt_pk_bf16_f32 v36, v243, v244
	v_cvt_pk_bf16_f32 v37, v245, v246
	v_cvt_pk_bf16_f32 v39, v44, v45
	v_cvt_pk_bf16_f32 v40, v46, v47
	v_cvt_pk_bf16_f32 v41, v48, v49
	v_add_f32_e32 v42, v49, v42
	s_waitcnt vmcnt(8)
	s_setprio 1
	v_mfma_f32_32x32x16_bf16 v[18:33], v[126:129], v[34:37], v[18:33]
	v_mfma_f32_32x32x16_bf16 v[2:17], v[118:121], v[34:37], v[2:17]
	v_mfma_f32_32x32x16_bf16 v[18:33], v[122:125], v[38:41], v[18:33]
	v_mfma_f32_32x32x16_bf16 v[2:17], v[114:117], v[38:41], v[2:17]
	s_setprio 0
	v_add_f32_e32 v171, v171, v42
	s_cmp_lt_u32 s6, 7
	s_cbranch_scc0 .Lattn_novA
	v_lshl_add_u64 v[252:253], v[200:201], 0, s[10:11]
	global_load_dwordx4 v[126:129], v[252:253], off
	global_load_dwordx4 v[122:125], v[252:253], off offset:1024
	global_load_dwordx4 v[118:121], v[252:253], off offset:2048
	global_load_dwordx4 v[114:117], v[252:253], off offset:3072
.Lattn_novA:
	s_add_i32 s7, s6, 1
	s_cmp_lt_u32 s6, 7
	s_cselect_b64 s[10:11], -1, 0
	s_and_b64 s[0:1], s[0:1], s[10:11]
	v_add_u32_e32 v0, 0x80, v0
	s_and_b64 vcc, exec, s[0:1]
	s_cbranch_vccz .LBB0_446
	s_mov_b32 s6, s7
	s_branch .Lattn_hdrB
.Lattn_hdrB:
	s_add_i32 s7, s53, s6
	s_cmp_le_u32 s7, s52
	s_cselect_b64 s[0:1], -1, 0
	s_cmp_gt_u32 s7, s52
	s_cbranch_scc1 .LBB0_446
	s_add_i32 s60, s7, 2
	s_min_i32 s40, s60, s52
	s_lshl_b64 s[10:11], s[40:41], 12
	s_waitcnt vmcnt(12)
	ds_read_u16 v154, v0
	s_setprio 1
	v_mfma_f32_32x32x16_bf16 v[34:49], v[66:69], v[98:101], 0
	v_mfma_f32_32x32x16_bf16 v[34:49], v[70:73], v[102:105], v[34:49]
	v_mfma_f32_32x32x16_bf16 v[34:49], v[74:77], v[106:109], v[34:49]
	v_mfma_f32_32x32x16_bf16 v[34:49], v[78:81], v[110:113], v[34:49]
	s_setprio 0
	s_cmp_lt_u32 s6, 7
	s_cbranch_scc0 .Lattn_nokB
	v_lshl_add_u64 v[252:253], v[198:199], 0, s[10:11]
	global_load_dwordx4 v[66:69], v[252:253], off
	global_load_dwordx4 v[70:73], v[252:253], off offset:1024
	global_load_dwordx4 v[74:77], v[252:253], off offset:2048
	global_load_dwordx4 v[78:81], v[252:253], off offset:3072

; #define MFMA(a, b, c) __builtin_amdgcn_mfma_f32_32x32x16_bf16((a), (b), (c), 0, 0, 0)
; DI void dsa_attn_item(const Params& p, int b, int qblk, char* smem) {
;     ...
;       const float msafe = (mrun == -INFINITY) ? 0.f : mrun;
;       float pv[16]; float ps = 0.f;
; #pragma unroll
;       for (int i = 0; i < 16; ++i) { pv[i] = __builtin_amdgcn_exp2f(sm[i] - msafe); ps += pv[i]; }
;       lrun += ps;
;       bf16x8 Pf[2];
; #pragma unroll
;       for (int s = 0; s < 2; ++s) Pf[s] = pack8(pv[8 * s], pv[8 * s + 1], pv[8 * s + 2], pv[8 * s + 3], pv[8 * s + 4], pv[8 * s + 5], pv[8 * s + 6], pv[8 * s + 7]);
;       __builtin_amdgcn_s_setprio(1);
; #pragma unroll
;       for (int dt = 0; dt < 2; ++dt)
; #pragma unroll
;         for (int s = 0; s < 2; ++s) O[dt] = MFMA(Vf[dt][s], Pf[s], O[dt]);
;       __builtin_amdgcn_s_setprio(0);
; #pragma unroll
;       for (int ks = 0; ks < 4; ++ks) Kf[ks] = Kn[ks];
; #pragma unroll
;       for (int dt = 0; dt < 2; ++dt)
; #pragma unroll
;         for (int s = 0; s < 2; ++s) Vf[dt][s] = Vn[dt][s];
.Lattn_442B:
	v_cmp_neq_f32_e32 vcc, s50, v193
	s_nop 1
	v_cndmask_b32_e32 v238, 0, v193, vcc
	v_sub_f32_e32 v34, v34, v238
	v_exp_f32_e32 v239, v34
	v_sub_f32_e32 v34, v35, v238
	v_exp_f32_e32 v240, v34
	v_sub_f32_e32 v34, v36, v238
	v_exp_f32_e32 v241, v34
	v_sub_f32_e32 v34, v37, v238
	v_exp_f32_e32 v242, v34
	v_sub_f32_e32 v34, v38, v238
	v_exp_f32_e32 v243, v34
	v_sub_f32_e32 v34, v39, v238
	v_exp_f32_e32 v244, v34
	v_sub_f32_e32 v34, v40, v238
	v_exp_f32_e32 v245, v34
	v_sub_f32_e32 v34, v41, v238
	v_exp_f32_e32 v246, v34
	v_sub_f32_e32 v34, v42, v238
	v_exp_f32_e32 v42, v34
	v_sub_f32_e32 v34, v43, v238
	v_exp_f32_e32 v43, v34
	v_sub_f32_e32 v34, v44, v238
	v_exp_f32_e32 v44, v34
	v_sub_f32_e32 v34, v45, v238
	v_exp_f32_e32 v45, v34
	v_sub_f32_e32 v34, v46, v238
	v_exp_f32_e32 v46, v34
	v_sub_f32_e32 v34, v47, v238
	v_exp_f32_e32 v47, v34
	v_sub_f32_e32 v34, v48, v238
	v_exp_f32_e32 v48, v34
	v_sub_f32_e32 v34, v49, v238
	v_add_f32_e32 v238, 0, v239
	v_add_f32_e32 v238, v240, v238
	v_add_f32_e32 v238, v241, v238
	v_add_f32_e32 v238, v242, v238
	v_add_f32_e32 v238, v243, v238
	v_add_f32_e32 v238, v244, v238
	v_add_f32_e32 v238, v245, v238
	v_add_f32_e32 v238, v246, v238
	v_cvt_pk_bf16_f32 v38, v42, v43
	v_add_f32_e32 v42, v42, v238
	v_add_f32_e32 v42, v43, v42
	v_add_f32_e32 v42, v44, v42
	v_exp_f32_e32 v49, v34
	v_add_f32_e32 v42, v45, v42
	v_add_f32_e32 v42, v46, v42
	v_add_f32_e32 v42, v47, v42
	v_add_f32_e32 v42, v48, v42
	v_cvt_pk_bf16_f32 v34, v239, v240
	v_cvt_pk_bf16_f32 v35, v241, v242
	v_cvt_pk_bf16_f32 v36, v243, v244
	v_cvt_pk_bf16_f32 v37, v245, v246
	v_cvt_pk_bf16_f32 v39, v44, v45
	v_cvt_pk_bf16_f32 v40, v46, v47
	v_cvt_pk_bf16_f32 v41, v48, v49
	v_add_f32_e32 v42, v49, v42
	s_waitcnt vmcnt(8)
	s_setprio 1
	v_mfma_f32_32x32x16_bf16 v[18:33], v[50:53], v[34:37], v[18:33]
	v_mfma_f32_32x32x16_bf16 v[2:17], v[58:61], v[34:37], v[2:17]
	v_mfma_f32_32x32x16_bf16 v[18:33], v[54:57], v[38:41], v[18:33]
	v_mfma_f32_32x32x16_bf16 v[2:17], v[62:65], v[38:41], v[2:17]
	s_setprio 0
	v_add_f32_e32 v171, v171, v42
	s_cmp_lt_u32 s6, 7
	s_cbranch_scc0 .Lattn_novB
	v_lshl_add_u64 v[252:253], v[200:201], 0, s[10:11]
	global_load_dwordx4 v[50:53], v[252:253], off
	global_load_dwordx4 v[54:57], v[252:253], off offset:1024
	global_load_dwordx4 v[58:61], v[252:253], off offset:2048
	global_load_dwordx4 v[62:65], v[252:253], off offset:3072

; DI void dsa_attn_item(const Params& p, int b, int qblk, char* smem) {
;     ...
;   for (int c = 0; c < nchunks; ++c) {
;     const int buf = c & 1;
;     {
;       const int key0 = (c * 8 + wave) * 32;
;       unsigned bits = 0u;
;       const bf16x8 k0 = ki0, k1 = ki1;
;       {
;         const int ktn = min((c + 1) * 8 + wave, qblk);
;         ki0 = ldg8(kibase + (size_t)ktn * 1024); ki1 = ldg8(kibase + (size_t)ktn * 1024 + 512);
;       }
.LBB0_446:
	s_xor_b64 s[44:45], s[44:45], -1
	s_add_i32 s53, s53, 8
	s_cmp_lg_u32 s54, s5
	s_cbranch_scc0 .LBB0_424
	s_waitcnt vmcnt(8)
	v_mov_b64_e32 v[156:157], v[132:133]
	v_mov_b64_e32 v[160:161], v[136:137]
	v_mov_b64_e32 v[154:155], v[130:131]
	v_mov_b64_e32 v[158:159], v[134:135]
	s_mov_b32 s54, s55
	s_branch .LBB0_434

; DI float bflo(unsigned u) { return __uint_as_float(u << 16); }
; DI float bfhi(unsigned u) { return __uint_as_float(u & 0xffff0000u); }
; DI void gla_g3_item(const Params& p, int item, char* smem) {
;     ...
;   const float tot = red[(ct * 4 + 0) * 32 + lr] + red[(ct * 4 + 1) * 32 + lr] + red[(ct * 4 + 2) * 32 + lr] + red[(ct * 4 + 3) * 32 + lr];
;   const float rinv = rsqrtf(tot * (1.f / 128.f) + 1e-6f);
;   const int tok = tok0 + ct * 32 + lr;
;   u16* y = (u16*)(p.ws + OFF_XB);
; #pragma unroll
;   for (int g = 0; g < 4; ++g) {
;     const int e0 = et * 32 + 8 * g + 4 * lh;
;     u32x2 gr = *reinterpret_cast<const u32x2*>(tm + (size_t)tok * TMW + TM_GR + h * 128 + e0);
;     f32x4 ng = *reinterpret_cast<const f32x4*>(p.norm_g + e0);
;     float grv[4] = {bflo(gr[0]), bfhi(gr[0]), bflo(gr[1]), bfhi(gr[1])};
;     float o[4];
; #pragma unroll
;     for (int r = 0; r < 4; ++r) {
;       float sl = grv[r] / (1.f + __expf(-grv[r]));
;       o[r] = O[4 * g + r] * rinv * ng[r] * sl;
;     }
;     st4bf(y + (size_t)tok * 1024 + 512 + h * 128 + e0, o[0], o[1], o[2], o[3]);
;   }
.LBB0_507:
	s_or_b64 exec, exec, s[54:55]
	s_waitcnt lgkmcnt(0)
	s_barrier
	ds_read2_b32 v[16:17], v135 offset1:32
	v_ashrrev_i32_e32 v129, 31, v128
	s_lshl_b32 s86, s86, 1
	v_lshlrev_b64 v[20:21], 11, v[128:129]
	v_lshl_add_u64 v[20:21], s[96:97], 0, v[20:21]
	s_waitcnt lgkmcnt(0)
	v_add_f32_e32 v18, v16, v17
	ds_read2_b32 v[16:17], v135 offset0:64 offset1:96
	v_lshl_add_u64 v[24:25], v[20:21], 0, s[86:87]
	s_mov_b32 s4, 0x800000
	s_add_i32 s79, s79, s78
	s_add_i32 s93, s93, s95
	s_waitcnt lgkmcnt(0)
	v_add_f32_e32 v16, v18, v16
	v_lshl_add_u64 v[18:19], v[130:131], 0, s[86:87]
	v_lshl_add_u64 v[18:19], v[18:19], 0, v[108:109]
	global_load_dwordx2 v[26:27], v[18:19], off offset:3712
	global_load_dwordx4 v[20:23], v[110:111], off
	global_load_dwordx2 v[184:185], v[18:19], off offset:3728
	global_load_dwordx4 v[188:191], v[110:111], off offset:32
	global_load_dwordx2 v[186:187], v[18:19], off offset:3744
	global_load_dwordx4 v[192:195], v[110:111], off offset:64
	global_load_dwordx2 v[196:197], v[18:19], off offset:3760
	global_load_dwordx4 v[200:203], v[110:111], off offset:96
	v_add_f32_e32 v16, v16, v17
	v_fmamk_f32 v16, v16, 0x3c000000, v137
	v_cmp_gt_f32_e32 vcc, s4, v16
	v_mul_f32_e32 v17, 0x4b800000, v16
	s_add_u32 s90, s90, s88
	v_cndmask_b32_e32 v16, v16, v17, vcc
	v_rsq_f32_e32 v16, v16
	s_addc_u32 s91, s91, s89
	s_cmpk_gt_i32 s79, 0x7ff
	v_mul_f32_e32 v17, 0x45800000, v16
	v_cndmask_b32_e32 v16, v16, v17, vcc
	s_waitcnt vmcnt(7)
	v_lshlrev_b32_e32 v17, 16, v26
	v_and_b32_e32 v26, 0xffff0000, v26
	v_mul_f32_e32 v28, 0xbfb8aa3b, v17
	v_mul_f32_e32 v29, 0xbfb8aa3b, v26
	v_exp_f32_e32 v28, v28
	v_exp_f32_e32 v29, v29
	v_pk_mul_f32 v[0:1], v[0:1], v[16:17] op_sel_hi:[1,0]
	v_pk_add_f32 v[28:29], v[28:29], 1.0 op_sel_hi:[1,0]
	s_nop 0
	v_div_scale_f32 v30, s[4:5], v29, v29, v26
	v_rcp_f32_e32 v31, v30
	s_waitcnt vmcnt(6)
	v_pk_mul_f32 v[0:1], v[20:21], v[0:1]
	v_fma_f32 v32, -v30, v31, 1.0
	v_fmac_f32_e32 v31, v32, v31
	v_div_scale_f32 v32, vcc, v26, v29, v26
	v_mul_f32_e32 v33, v32, v31
	v_fma_f32 v34, -v30, v33, v32
	v_fmac_f32_e32 v33, v34, v31
	v_fma_f32 v30, -v30, v33, v32
	v_div_fmas_f32 v30, v30, v31, v33
	v_div_fixup_f32 v29, v30, v29, v26
	v_div_scale_f32 v26, s[4:5], v28, v28, v17
	v_rcp_f32_e32 v30, v26
	s_nop 0
	v_fma_f32 v31, -v26, v30, 1.0
	v_fmac_f32_e32 v30, v31, v30
	v_div_scale_f32 v31, vcc, v17, v28, v17
	v_mul_f32_e32 v32, v31, v30
	v_fma_f32 v33, -v26, v32, v31
	v_fmac_f32_e32 v32, v33, v30
	v_fma_f32 v26, -v26, v32, v31
	v_div_fmas_f32 v26, v26, v30, v32
	v_div_fixup_f32 v28, v26, v28, v17
	v_lshlrev_b32_e32 v17, 16, v27
	v_and_b32_e32 v26, 0xffff0000, v27
	v_pk_mul_f32 v[20:21], v[28:29], v[0:1]
	v_mul_f32_e32 v0, 0xbfb8aa3b, v17
	v_mul_f32_e32 v1, 0xbfb8aa3b, v26
	v_exp_f32_e32 v0, v0
	v_exp_f32_e32 v1, v1
	v_pk_mul_f32 v[2:3], v[2:3], v[16:17] op_sel_hi:[1,0]
	v_cvt_pk_bf16_f32 v20, v20, v21
	v_pk_mul_f32 v[2:3], v[22:23], v[2:3]
	v_pk_add_f32 v[0:1], v[0:1], 1.0 op_sel_hi:[1,0]
	s_nop 0
	v_div_scale_f32 v27, s[4:5], v1, v1, v26
	v_rcp_f32_e32 v28, v27
	s_nop 0
	v_fma_f32 v29, -v27, v28, 1.0
	v_fmac_f32_e32 v28, v29, v28
	v_div_scale_f32 v29, vcc, v26, v1, v26
	v_mul_f32_e32 v30, v29, v28
	v_fma_f32 v31, -v27, v30, v29
	v_fmac_f32_e32 v30, v31, v28
	v_fma_f32 v27, -v27, v30, v29
	v_div_fmas_f32 v27, v27, v28, v30
	v_div_fixup_f32 v1, v27, v1, v26
	v_div_scale_f32 v26, s[4:5], v0, v0, v17
	v_rcp_f32_e32 v27, v26
	s_nop 0
	v_fma_f32 v28, -v26, v27, 1.0
	v_fmac_f32_e32 v27, v28, v27
	v_div_scale_f32 v28, vcc, v17, v0, v17
	v_mul_f32_e32 v29, v28, v27
	v_fma_f32 v30, -v26, v29, v28
	v_fmac_f32_e32 v29, v30, v27
	v_fma_f32 v26, -v26, v29, v28
	v_div_fmas_f32 v26, v26, v27, v29
	v_div_fixup_f32 v0, v26, v0, v17
	v_pk_mul_f32 v[2:3], v[0:1], v[2:3]
	v_lshl_add_u64 v[0:1], v[24:25], 0, v[108:109]
	v_cvt_pk_bf16_f32 v21, v2, v3
	global_store_dwordx2 v[0:1], v[20:21], off offset:1024
	s_nop 0
	s_waitcnt vmcnt(6)
	v_lshlrev_b32_e32 v17, 16, v184
	v_and_b32_e32 v2, 0xffff0000, v184
	v_mul_f32_e32 v24, 0xbfb8aa3b, v17
	v_mul_f32_e32 v25, 0xbfb8aa3b, v2
	v_exp_f32_e32 v24, v24
	v_exp_f32_e32 v25, v25
	v_pk_mul_f32 v[4:5], v[4:5], v[16:17] op_sel_hi:[1,0]
	v_pk_add_f32 v[24:25], v[24:25], 1.0 op_sel_hi:[1,0]
	s_nop 0
	v_div_scale_f32 v26, s[4:5], v25, v25, v2
	v_rcp_f32_e32 v27, v26
	s_waitcnt vmcnt(5)
	v_pk_mul_f32 v[4:5], v[188:189], v[4:5]
	v_and_b32_e32 v20, 0xffff0000, v185
	v_fma_f32 v28, -v26, v27, 1.0
	v_fmac_f32_e32 v27, v28, v27
	v_div_scale_f32 v28, vcc, v2, v25, v2
	v_mul_f32_e32 v29, v28, v27
	v_fma_f32 v30, -v26, v29, v28
	v_fmac_f32_e32 v29, v30, v27
	v_fma_f32 v26, -v26, v29, v28
	v_div_fmas_f32 v26, v26, v27, v29
	v_div_fixup_f32 v25, v26, v25, v2
	v_div_scale_f32 v2, s[4:5], v24, v24, v17
	v_rcp_f32_e32 v26, v2
	s_nop 0
	v_fma_f32 v27, -v2, v26, 1.0
	v_fmac_f32_e32 v26, v27, v26
	v_div_scale_f32 v27, vcc, v17, v24, v17
	v_mul_f32_e32 v28, v27, v26
	v_fma_f32 v29, -v2, v28, v27
	v_fmac_f32_e32 v28, v29, v26
	v_fma_f32 v2, -v2, v28, v27
	v_div_fmas_f32 v2, v2, v26, v28
	v_div_fixup_f32 v24, v2, v24, v17
	v_lshlrev_b32_e32 v17, 16, v185
	v_mul_f32_e32 v2, 0xbfb8aa3b, v17
	v_mul_f32_e32 v3, 0xbfb8aa3b, v20
	v_exp_f32_e32 v2, v2
	v_exp_f32_e32 v3, v3
	v_pk_mul_f32 v[4:5], v[4:5], v[24:25]
	v_pk_mul_f32 v[6:7], v[6:7], v[16:17] op_sel_hi:[1,0]
	v_cvt_pk_bf16_f32 v4, v4, v5
	v_pk_add_f32 v[2:3], v[2:3], 1.0 op_sel_hi:[1,0]
	v_pk_mul_f32 v[6:7], v[190:191], v[6:7]
	v_div_scale_f32 v21, s[4:5], v3, v3, v20
	v_rcp_f32_e32 v24, v21
	s_nop 0
	v_fma_f32 v25, -v21, v24, 1.0
	v_fmac_f32_e32 v24, v25, v24
	v_div_scale_f32 v25, vcc, v20, v3, v20
	v_mul_f32_e32 v26, v25, v24
	v_fma_f32 v27, -v21, v26, v25
	v_fmac_f32_e32 v26, v27, v24
	v_fma_f32 v21, -v21, v26, v25
	v_div_fmas_f32 v21, v21, v24, v26
	v_div_fixup_f32 v3, v21, v3, v20
	v_div_scale_f32 v20, s[4:5], v2, v2, v17
	v_rcp_f32_e32 v21, v20
	s_nop 0
	v_fma_f32 v24, -v20, v21, 1.0
	v_fmac_f32_e32 v21, v24, v21
	v_div_scale_f32 v24, vcc, v17, v2, v17
	v_mul_f32_e32 v25, v24, v21
	v_fma_f32 v26, -v20, v25, v24
	v_fmac_f32_e32 v25, v26, v21
	v_fma_f32 v20, -v20, v25, v24
	v_div_fmas_f32 v20, v20, v21, v25
	v_div_fixup_f32 v2, v20, v2, v17
	v_pk_mul_f32 v[2:3], v[6:7], v[2:3]
	s_nop 0
	v_cvt_pk_bf16_f32 v5, v2, v3
	global_store_dwordx2 v[0:1], v[4:5], off offset:1040
	s_nop 0
	s_waitcnt vmcnt(5)
; DI float bflo(unsigned u) { return __uint_as_float(u << 16); }
; DI float bfhi(unsigned u) { return __uint_as_float(u & 0xffff0000u); }
; DI void gla_g3_item(const Params& p, int item, char* smem) {
;     ...
; #pragma unroll
;   for (int g = 0; g < 4; ++g) {
;     const int e0 = et * 32 + 8 * g + 4 * lh;
;     u32x2 gr = *reinterpret_cast<const u32x2*>(tm + (size_t)tok * TMW + TM_GR + h * 128 + e0);
;     f32x4 ng = *reinterpret_cast<const f32x4*>(p.norm_g + e0);
;     float grv[4] = {bflo(gr[0]), bfhi(gr[0]), bflo(gr[1]), bfhi(gr[1])};
;     float o[4];
; #pragma unroll
;     for (int r = 0; r < 4; ++r) {
;       float sl = grv[r] / (1.f + __expf(-grv[r]));
;       o[r] = O[4 * g + r] * rinv * ng[r] * sl;
;     }
;     st4bf(y + (size_t)tok * 1024 + 512 + h * 128 + e0, o[0], o[1], o[2], o[3]);
;   }
;   __syncthreads();
	v_lshlrev_b32_e32 v17, 16, v186
	v_and_b32_e32 v6, 0xffff0000, v186
	v_mul_f32_e32 v20, 0xbfb8aa3b, v17
	v_mul_f32_e32 v21, 0xbfb8aa3b, v6
	v_exp_f32_e32 v20, v20
	v_exp_f32_e32 v21, v21
	v_pk_mul_f32 v[8:9], v[8:9], v[16:17] op_sel_hi:[1,0]
	v_pk_add_f32 v[20:21], v[20:21], 1.0 op_sel_hi:[1,0]
	s_nop 0
	v_div_scale_f32 v22, s[4:5], v21, v21, v6
	v_rcp_f32_e32 v23, v22
	s_waitcnt vmcnt(4)
	v_pk_mul_f32 v[2:3], v[192:193], v[8:9]
	v_lshlrev_b32_e32 v8, 16, v187
	v_and_b32_e32 v9, 0xffff0000, v187
	v_fma_f32 v24, -v22, v23, 1.0
	v_fmac_f32_e32 v23, v24, v23
	v_div_scale_f32 v24, vcc, v6, v21, v6
	v_mul_f32_e32 v25, v24, v23
	v_fma_f32 v26, -v22, v25, v24
	v_fmac_f32_e32 v25, v26, v23
	v_fma_f32 v22, -v22, v25, v24
	v_div_fmas_f32 v22, v22, v23, v25
	v_div_fixup_f32 v21, v22, v21, v6
	v_div_scale_f32 v6, s[4:5], v20, v20, v17
	v_rcp_f32_e32 v22, v6
	v_mul_f32_e32 v7, 0xbfb8aa3b, v9
	v_exp_f32_e32 v7, v7
	v_fma_f32 v23, -v6, v22, 1.0
	v_fmac_f32_e32 v22, v23, v22
	v_div_scale_f32 v23, vcc, v17, v20, v17
	v_mul_f32_e32 v24, v23, v22
	v_fma_f32 v25, -v6, v24, v23
	v_fmac_f32_e32 v24, v25, v22
	v_fma_f32 v6, -v6, v24, v23
	v_div_fmas_f32 v6, v6, v22, v24
	v_div_fixup_f32 v20, v6, v20, v17
	v_mul_f32_e32 v6, 0xbfb8aa3b, v8
	v_exp_f32_e32 v6, v6
	v_pk_mul_f32 v[2:3], v[2:3], v[20:21]
	v_pk_add_f32 v[6:7], v[6:7], 1.0 op_sel_hi:[1,0]
	s_nop 0
	v_div_scale_f32 v17, s[4:5], v7, v7, v9
	v_rcp_f32_e32 v20, v17
	v_cvt_pk_bf16_f32 v2, v2, v3
	v_fma_f32 v21, -v17, v20, 1.0
	v_fmac_f32_e32 v20, v21, v20
	v_div_scale_f32 v21, vcc, v9, v7, v9
	v_mul_f32_e32 v22, v21, v20
	v_fma_f32 v23, -v17, v22, v21
	v_fmac_f32_e32 v22, v23, v20
	v_fma_f32 v17, -v17, v22, v21
	v_div_fmas_f32 v17, v17, v20, v22
	v_div_fixup_f32 v7, v17, v7, v9
	v_div_scale_f32 v9, s[4:5], v6, v6, v8
	v_rcp_f32_e32 v17, v9
	s_nop 0
	v_fma_f32 v20, -v9, v17, 1.0
	v_fmac_f32_e32 v17, v20, v17
	v_div_scale_f32 v20, vcc, v8, v6, v8
	v_mul_f32_e32 v21, v20, v17
	v_fma_f32 v22, -v9, v21, v20
	v_fmac_f32_e32 v21, v22, v17
	v_fma_f32 v9, -v9, v21, v20
	v_div_fmas_f32 v9, v9, v17, v21
	v_div_fixup_f32 v6, v9, v6, v8
	v_pk_mul_f32 v[8:9], v[10:11], v[16:17] op_sel_hi:[1,0]
	s_nop 0
	v_pk_mul_f32 v[4:5], v[194:195], v[8:9]
	s_nop 0
	v_pk_mul_f32 v[4:5], v[4:5], v[6:7]
	s_nop 0
	v_cvt_pk_bf16_f32 v3, v4, v5
	global_store_dwordx2 v[0:1], v[2:3], off offset:1056
	s_nop 0
	s_waitcnt vmcnt(4)
	v_lshlrev_b32_e32 v10, 16, v196
	v_and_b32_e32 v2, 0xffff0000, v196
	v_mul_f32_e32 v8, 0xbfb8aa3b, v10
	v_mul_f32_e32 v9, 0xbfb8aa3b, v2
	v_exp_f32_e32 v8, v8
	v_exp_f32_e32 v9, v9
	s_nop 0
	v_pk_add_f32 v[8:9], v[8:9], 1.0 op_sel_hi:[1,0]
	s_nop 0
	v_div_scale_f32 v11, s[4:5], v9, v9, v2
	v_rcp_f32_e32 v17, v11
	s_nop 0
	v_fma_f32 v18, -v11, v17, 1.0
	v_fmac_f32_e32 v17, v18, v17
	v_div_scale_f32 v18, vcc, v2, v9, v2
	v_mul_f32_e32 v19, v18, v17
	v_fma_f32 v20, -v11, v19, v18
	v_fmac_f32_e32 v19, v20, v17
	v_fma_f32 v11, -v11, v19, v18
	v_div_fmas_f32 v11, v11, v17, v19
	v_div_fixup_f32 v9, v11, v9, v2
	v_div_scale_f32 v2, s[4:5], v8, v8, v10
	v_rcp_f32_e32 v11, v2
	s_nop 0
	v_fma_f32 v17, -v2, v11, 1.0
	v_fmac_f32_e32 v11, v17, v11
	v_div_scale_f32 v17, vcc, v10, v8, v10
	v_mul_f32_e32 v18, v17, v11
	v_fma_f32 v19, -v2, v18, v17
	v_fmac_f32_e32 v18, v19, v11
	v_fma_f32 v2, -v2, v18, v17
	v_div_fmas_f32 v2, v2, v11, v18
	v_div_fixup_f32 v8, v2, v8, v10
	v_pk_mul_f32 v[10:11], v[12:13], v[16:17] op_sel_hi:[1,0]
	s_waitcnt vmcnt(3)
	v_pk_mul_f32 v[4:5], v[10:11], v[200:201]
	s_nop 0
	v_pk_mul_f32 v[4:5], v[4:5], v[8:9]
	v_lshlrev_b32_e32 v8, 16, v197
	v_and_b32_e32 v9, 0xffff0000, v197
	v_mul_f32_e32 v2, 0xbfb8aa3b, v8
	v_mul_f32_e32 v3, 0xbfb8aa3b, v9
	v_exp_f32_e32 v2, v2
	v_exp_f32_e32 v3, v3
	v_cvt_pk_bf16_f32 v4, v4, v5
	v_pk_add_f32 v[2:3], v[2:3], 1.0 op_sel_hi:[1,0]
	s_nop 0
	v_div_scale_f32 v10, s[4:5], v3, v3, v9
	v_rcp_f32_e32 v11, v10
	s_nop 0
	v_fma_f32 v12, -v10, v11, 1.0
	v_fmac_f32_e32 v11, v12, v11
	v_div_scale_f32 v12, vcc, v9, v3, v9
	v_mul_f32_e32 v13, v12, v11
	v_fma_f32 v17, -v10, v13, v12
	v_fmac_f32_e32 v13, v17, v11
	v_fma_f32 v10, -v10, v13, v12
	v_div_fmas_f32 v10, v10, v11, v13
	v_div_fixup_f32 v3, v10, v3, v9
	v_div_scale_f32 v9, s[4:5], v2, v2, v8
	v_rcp_f32_e32 v10, v9
	s_nop 0
	v_fma_f32 v11, -v9, v10, 1.0
	v_fmac_f32_e32 v10, v11, v10
	v_div_scale_f32 v11, vcc, v8, v2, v8
	v_mul_f32_e32 v12, v11, v10
	v_fma_f32 v13, -v9, v12, v11
	v_fmac_f32_e32 v12, v13, v10
	v_fma_f32 v9, -v9, v12, v11
	v_div_fmas_f32 v9, v9, v10, v12
	v_div_fixup_f32 v2, v9, v2, v8
	v_pk_mul_f32 v[8:9], v[14:15], v[16:17] op_sel_hi:[1,0]
	s_nop 0
	v_pk_mul_f32 v[6:7], v[8:9], v[202:203]
	s_nop 0
	v_pk_mul_f32 v[2:3], v[6:7], v[2:3]
	s_nop 0
	v_cvt_pk_bf16_f32 v5, v2, v3
	global_store_dwordx2 v[0:1], v[4:5], off offset:1072
	s_barrier
	s_cbranch_scc1 .LBB0_512
